# speedup vs baseline: 1.0067x; 1.0067x over previous
; #define PG8_STAGE(bufoff, gbase, voff) do { _Pragma("unroll") for (int _i = 0; _i < 2; ++_i) \
;         __builtin_amdgcn_global_load_lds((const unsigned*)((const char*)(gbase) + (voff)[_i]), (LAS unsigned*)(lds + (bufoff) + ldsw + _i * 8192), 16, 0, 0); } while (0)
; #define PG8_LDA(dst, b, h) do { _Pragma("unroll") for (int m = 0; m < 4; ++m) _Pragma("unroll") for (int k = 0; k < 2; ++k) dst[m][k] = *(const LAS bf16x8*)(lds + PG8_SA(b, h) + aoff + m * 2048 + k * 1024); } while (0)
; #define PG8_LDB(dst, b, h) do { _Pragma("unroll") for (int n = 0; n < 2; ++n) _Pragma("unroll") for (int k = 0; k < 2; ++k) dst[n][k] = *(const LAS bf16x8*)(lds + PG8_SB(b, h) + boff + n * 2048 + k * 1024); } while (0)
; #define PG8_MMA(ai, bj, At, Bt) do { __builtin_amdgcn_s_setprio(1); _Pragma("unroll") for (int m = 0; m < 4; ++m) _Pragma("unroll") for (int n = 0; n < 2; ++n) _Pragma("unroll") for (int k = 0; k < 2; ++k) \
;         acc[ai][bj][m][n] = __builtin_amdgcn_mfma_f32_16x16x32_bf16(Bt[n][k], At[m][k], acc[ai][bj][m][n], 0, 0, 0); __builtin_amdgcn_s_setprio(0); } while (0)
; #define PG8_WAIT_V(n) asm volatile("s_waitcnt vmcnt(" #n ")" ::: "memory")
;     __host__ __device__ bool next(int i, Unit& u) const {
;         const long L = (long)i * G + c; if (L >= nwg) return false;
;         int wgid = (int)L; { const int q = nwg / NXCD, r = nwg % NXCD, xcd = wgid % NXCD, off = wgid / NXCD; wgid = (xcd < r ? xcd * (q + 1) : r * (q + 1) + (xcd - r) * q) + off; }
;         const int nig = WGM * nN, gid = wgid / nig, fm = gid * WGM, gsz = (nM - fm) < WGM ? (nM - fm) : WGM;
;         u.pm = fm + ((wgid % nig) % gsz); u.pn = (wgid % nig) / gsz; return true;
; template <class Epi, class Pre, bool AG = false>
; __device__ __forceinline__ void gemm_phase(LAS unsigned char* lds, const Gemm g, const StaticOrder& S, const Epi& E, const Pre& P) {
;     ...
;             PG8_LDB(B0, 0, 0); PG8_LDB(B1, 0, 1); PG8_SCHED; PG8_LDA(At, 0, 0); PG8_STAGE(PG8_SA(1, 1), a1 + hstepA, voffA);
;             PG8_WAIT_V(8); PG8_WAIT_L(0); PG8_BAR; PG8_MMA(0, 0, At, B0); PG8_MMA(0, 1, At, B1); PG8_BAR; PG8_SCHED;
;             PG8_LDA(At, 0, 1); PG8_STAGE(PG8_SB(0, 0), b2, voffB); PG8_STAGE(PG8_SB(0, 1), b2 + hstep, voffB); PG8_STAGE(PG8_SA(0, 0), a2, voffA);
;             PG8_WAIT_V(8); PG8_WAIT_L(0); PG8_BAR; PG8_MMA(1, 0, At, B0); PG8_MMA(1, 1, At, B1); PG8_BAR; PG8_SCHED;
.LBB0_209:
	s_add_i32 s61, s70, 1
	s_mul_i32 s6, s61, s19
	s_mul_hi_u32 s7, s61, s18
	s_add_i32 s7, s7, s6
	s_mul_i32 s6, s61, s18
	s_add_u32 s12, s6, s2
	s_addc_u32 s13, s7, s3
	v_cmp_gt_i64_e32 vcc, s[12:13], v[232:233]
	v_cmp_lt_i64_e64 s[6:7], s[12:13], v[236:237]
	s_cbranch_vccnz .LBB0_211
	s_and_b32 s13, s12, 7
	s_mul_i32 s13, s13, 0xb0
	s_lshr_b32 s16, s12, 3
	s_add_i32 s13, s13, s16
	s_mul_hi_u32 s16, s13, 0x2e8ba2e9
	s_lshr_b32 s16, s16, 4
	s_mul_i32 s17, s16, 0x58
	s_sub_i32 s13, s13, s17
	s_lshl_b32 s26, s16, 2
	s_and_b32 s17, s13, 3
	s_add_i32 s26, s26, s17
	s_lshr_b32 s16, s13, 2
.LBB0_211:
	s_ashr_i32 s27, s26, 31
	s_lshl_b64 s[12:13], s[26:27], 19
	s_add_u32 s28, s20, s12
	s_addc_u32 s29, s24, s13
	s_and_b64 s[12:13], s[6:7], exec
	s_cselect_b32 s12, s29, s45
	s_cselect_b32 s13, s28, s44
	s_ashr_i32 s17, s16, 31
	s_lshl_b64 s[42:43], s[16:17], 19
	s_add_u32 s42, s25, s42
	s_addc_u32 s43, s30, s43
	s_and_b64 s[54:55], s[6:7], exec
	s_cselect_b32 s17, s43, s47
	s_cselect_b32 s27, s42, s46
	s_add_u32 s44, s44, 0x40080
	s_addc_u32 s45, s45, 0
	s_add_u32 s76, s46, 0x100
	s_addc_u32 s77, s47, 0
	s_mov_b32 s79, -2
	s_add_u32 s46, s44, 0xfffc0080
	s_addc_u32 s47, s45, -1
	s_add_i32 s84, 0, 0x10000
	s_cmp_eq_u32 s79, 12
	s_cselect_b32 s55, s12, s47
	s_cselect_b32 s54, s13, s46
	s_cselect_b32 s47, s17, s77
	s_cselect_b32 s46, s27, s76
	s_add_i32 s86, 0, 0x14000
	v_add_u32_e32 v154, s84, v148
	v_add_u32_e32 v170, s86, v148
	ds_read_b128 v[140:143], v154
	ds_read_b128 v[144:147], v154 offset:1024
	ds_read_b128 v[150:153], v154 offset:2048
	ds_read_b128 v[154:157], v154 offset:3072
	ds_read_b128 v[158:161], v170
	ds_read_b128 v[162:165], v170 offset:1024
	ds_read_b128 v[166:169], v170 offset:2048
	ds_read_b128 v[170:173], v170 offset:3072
	v_lshl_add_u64 v[178:179], s[44:45], 0, v[0:1]
	s_add_i32 m0, s38, 0xc000
	ds_read_b128 v[174:177], v149
	ds_read_b128 v[194:197], v149 offset:1024
	ds_read_b128 v[198:201], v149 offset:2048
	ds_read_b128 v[202:205], v149 offset:3072
	ds_read_b128 v[206:209], v149 offset:4096
	ds_read_b128 v[210:213], v149 offset:5120
	ds_read_b128 v[214:217], v149 offset:6144
	ds_read_b128 v[218:221], v149 offset:7168
	global_load_lds_dwordx4 v[178:179], off
	v_lshl_add_u64 v[178:179], s[44:45], 0, v[138:139]
	s_add_i32 m0, s38, 0xe000
	s_nop 0
	global_load_lds_dwordx4 v[178:179], off
	s_cmp_eq_u32 s70, 0
	s_cbranch_scc1 .Lpw_gu_0
	s_waitcnt vmcnt(16)
	s_branch .Lpw_gu_0_done
.Lpw_gu_0:
	s_waitcnt vmcnt(8)
.Lpw_gu_0_done:
	s_waitcnt lgkmcnt(0)
	s_barrier
	s_setprio 1
	s_waitcnt lgkmcnt(0)
	v_mfma_f32_16x16x32_bf16 v[122:125], v[140:143], v[174:177], 0
	v_mfma_f32_16x16x32_bf16 v[114:117], v[150:153], v[174:177], 0
	v_mfma_f32_16x16x32_bf16 v[106:109], v[140:143], v[198:201], 0
	v_mfma_f32_16x16x32_bf16 v[98:101], v[150:153], v[198:201], 0
	v_mfma_f32_16x16x32_bf16 v[90:93], v[140:143], v[206:209], 0
	v_mfma_f32_16x16x32_bf16 v[82:85], v[150:153], v[206:209], 0
	v_mfma_f32_16x16x32_bf16 v[74:77], v[140:143], v[214:217], 0
	v_mfma_f32_16x16x32_bf16 v[66:69], v[150:153], v[214:217], 0
	v_mfma_f32_16x16x32_bf16 v[122:125], v[144:147], v[194:197], v[122:125]
	v_mfma_f32_16x16x32_bf16 v[114:117], v[154:157], v[194:197], v[114:117]
	v_mfma_f32_16x16x32_bf16 v[106:109], v[144:147], v[202:205], v[106:109]
	v_mfma_f32_16x16x32_bf16 v[98:101], v[154:157], v[202:205], v[98:101]
	v_mfma_f32_16x16x32_bf16 v[90:93], v[144:147], v[210:213], v[90:93]
	v_mfma_f32_16x16x32_bf16 v[82:85], v[154:157], v[210:213], v[82:85]
	v_mfma_f32_16x16x32_bf16 v[74:77], v[144:147], v[218:221], v[74:77]
	v_mfma_f32_16x16x32_bf16 v[66:69], v[154:157], v[218:221], v[66:69]
	s_setprio 0
	s_setprio 1
	v_mfma_f32_16x16x32_bf16 v[126:129], v[158:161], v[174:177], 0
	v_mfma_f32_16x16x32_bf16 v[118:121], v[166:169], v[174:177], 0
	v_mfma_f32_16x16x32_bf16 v[110:113], v[158:161], v[198:201], 0
	v_mfma_f32_16x16x32_bf16 v[102:105], v[166:169], v[198:201], 0
	v_mfma_f32_16x16x32_bf16 v[94:97], v[158:161], v[206:209], 0
	v_mfma_f32_16x16x32_bf16 v[86:89], v[166:169], v[206:209], 0
	v_mfma_f32_16x16x32_bf16 v[78:81], v[158:161], v[214:217], 0
	v_mfma_f32_16x16x32_bf16 v[70:73], v[166:169], v[214:217], 0
	v_mfma_f32_16x16x32_bf16 v[126:129], v[162:165], v[194:197], v[126:129]
	v_mfma_f32_16x16x32_bf16 v[118:121], v[170:173], v[194:197], v[118:121]
	v_mfma_f32_16x16x32_bf16 v[110:113], v[162:165], v[202:205], v[110:113]
	v_mfma_f32_16x16x32_bf16 v[102:105], v[170:173], v[202:205], v[102:105]
	v_mfma_f32_16x16x32_bf16 v[94:97], v[162:165], v[210:213], v[94:97]
	v_mfma_f32_16x16x32_bf16 v[86:89], v[170:173], v[210:213], v[86:89]
	v_mfma_f32_16x16x32_bf16 v[78:81], v[162:165], v[218:221], v[78:81]
	v_mfma_f32_16x16x32_bf16 v[70:73], v[170:173], v[218:221], v[70:73]
	s_setprio 0
	s_barrier
	s_add_i32 s84, s84, s31
	v_lshl_add_u64 v[178:179], s[46:47], 0, v[134:135]
	s_mov_b32 m0, s84
	ds_read_b128 v[174:177], v149 offset:16384
	ds_read_b128 v[194:197], v149 offset:17408
	ds_read_b128 v[198:201], v149 offset:18432
	ds_read_b128 v[202:205], v149 offset:19456
	ds_read_b128 v[206:209], v149 offset:20480
	ds_read_b128 v[210:213], v149 offset:21504
	ds_read_b128 v[214:217], v149 offset:22528
	ds_read_b128 v[218:221], v149 offset:23552
	global_load_lds_dwordx4 v[178:179], off
	s_add_i32 m0, s84, 0x2000
	s_add_u32 s84, s46, 0x40000
	v_lshl_add_u64 v[180:181], s[46:47], 0, v[130:131]
	s_addc_u32 s85, s47, 0
	s_add_i32 s86, s86, s31
	global_load_lds_dwordx4 v[180:181], off
	v_lshl_add_u64 v[182:183], s[84:85], 0, v[134:135]
	s_mov_b32 m0, s86
	v_lshl_add_u64 v[188:189], s[54:55], 0, v[132:133]
	global_load_lds_dwordx4 v[182:183], off
	v_lshl_add_u64 v[182:183], s[84:85], 0, v[130:131]
	s_add_i32 m0, s86, 0x2000
	s_nop 0
	global_load_lds_dwordx4 v[182:183], off
	v_lshl_add_u64 v[182:183], s[54:55], 0, v[136:137]
	s_mov_b32 m0, s38
	s_nop 0
	global_load_lds_dwordx4 v[182:183], off
	s_mov_b32 m0, s48
	s_nop 0
	global_load_lds_dwordx4 v[188:189], off
	s_cmp_eq_u32 s70, 0
	s_cbranch_scc1 .Lpw_gu_1
	s_waitcnt vmcnt(16)
	s_branch .Lpw_gu_1_done

; #define PG8_STAGE(bufoff, gbase, voff) do { _Pragma("unroll") for (int _i = 0; _i < 2; ++_i) \
;         __builtin_amdgcn_global_load_lds((const unsigned*)((const char*)(gbase) + (voff)[_i]), (LAS unsigned*)(lds + (bufoff) + ldsw + _i * 8192), 16, 0, 0); } while (0)
; #define PG8_LDA(dst, b, h) do { _Pragma("unroll") for (int m = 0; m < 4; ++m) _Pragma("unroll") for (int k = 0; k < 2; ++k) dst[m][k] = *(const LAS bf16x8*)(lds + PG8_SA(b, h) + aoff + m * 2048 + k * 1024); } while (0)
; #define PG8_LDB(dst, b, h) do { _Pragma("unroll") for (int n = 0; n < 2; ++n) _Pragma("unroll") for (int k = 0; k < 2; ++k) dst[n][k] = *(const LAS bf16x8*)(lds + PG8_SB(b, h) + boff + n * 2048 + k * 1024); } while (0)
; #define PG8_MMA(ai, bj, At, Bt) do { __builtin_amdgcn_s_setprio(1); _Pragma("unroll") for (int m = 0; m < 4; ++m) _Pragma("unroll") for (int n = 0; n < 2; ++n) _Pragma("unroll") for (int k = 0; k < 2; ++k) \
;         acc[ai][bj][m][n] = __builtin_amdgcn_mfma_f32_16x16x32_bf16(Bt[n][k], At[m][k], acc[ai][bj][m][n], 0, 0, 0); __builtin_amdgcn_s_setprio(0); } while (0)
; #define PG8_WAIT_V(n) asm volatile("s_waitcnt vmcnt(" #n ")" ::: "memory")
; #define PG8_WAIT_L(n) asm volatile("s_waitcnt lgkmcnt(" #n ")" ::: "memory")
; #define PG8_BAR __builtin_amdgcn_s_barrier()
; #define PG8_SCHED __builtin_amdgcn_sched_barrier(0)
; template <class Epi, class Pre, bool AG = false>
; __device__ __forceinline__ void gemm_phase(LAS unsigned char* lds, const Gemm g, const StaticOrder& S, const Epi& E, const Pre& P) {
;     ...
;             PG8_WAIT_V(8); PG8_WAIT_L(0); PG8_BAR; PG8_MMA(1, 0, At, B0); PG8_MMA(1, 1, At, B1); PG8_BAR; PG8_SCHED;
;             PG8_LDB(B0, 1, 0); PG8_LDB(B1, 1, 1); PG8_SCHED; PG8_LDA(At, 1, 0); PG8_STAGE(PG8_SA(0, 1), a2 + hstepA, voffA);
;             PG8_WAIT_V(8); PG8_WAIT_L(0); PG8_BAR; PG8_MMA(0, 0, At, B0); PG8_MMA(0, 1, At, B1); PG8_BAR; PG8_SCHED;
.Lpw_gu_1_done:
	s_waitcnt lgkmcnt(0)
	s_barrier
	s_setprio 1
	s_waitcnt lgkmcnt(0)
	v_mfma_f32_16x16x32_bf16 v[58:61], v[140:143], v[174:177], 0
	v_mfma_f32_16x16x32_bf16 v[50:53], v[150:153], v[174:177], 0
	v_mfma_f32_16x16x32_bf16 v[42:45], v[140:143], v[198:201], 0
	v_mfma_f32_16x16x32_bf16 v[34:37], v[150:153], v[198:201], 0
	v_mfma_f32_16x16x32_bf16 v[26:29], v[140:143], v[206:209], 0
	v_mfma_f32_16x16x32_bf16 v[18:21], v[150:153], v[206:209], 0
	v_mfma_f32_16x16x32_bf16 v[10:13], v[140:143], v[214:217], 0
	v_mfma_f32_16x16x32_bf16 v[6:9], v[150:153], v[214:217], 0
	v_mfma_f32_16x16x32_bf16 v[58:61], v[144:147], v[194:197], v[58:61]
	v_mfma_f32_16x16x32_bf16 v[50:53], v[154:157], v[194:197], v[50:53]
	v_mfma_f32_16x16x32_bf16 v[42:45], v[144:147], v[202:205], v[42:45]
	v_mfma_f32_16x16x32_bf16 v[34:37], v[154:157], v[202:205], v[34:37]
	v_mfma_f32_16x16x32_bf16 v[26:29], v[144:147], v[210:213], v[26:29]
	v_mfma_f32_16x16x32_bf16 v[18:21], v[154:157], v[210:213], v[18:21]
	v_mfma_f32_16x16x32_bf16 v[10:13], v[144:147], v[218:221], v[10:13]
	v_mfma_f32_16x16x32_bf16 v[6:9], v[154:157], v[218:221], v[6:9]
	s_setprio 0
	s_setprio 1
	v_mfma_f32_16x16x32_bf16 v[62:65], v[158:161], v[174:177], 0
	v_mfma_f32_16x16x32_bf16 v[54:57], v[166:169], v[174:177], 0
	v_mfma_f32_16x16x32_bf16 v[46:49], v[158:161], v[198:201], 0
	v_mfma_f32_16x16x32_bf16 v[38:41], v[166:169], v[198:201], 0
	v_mfma_f32_16x16x32_bf16 v[30:33], v[158:161], v[206:209], 0
	v_mfma_f32_16x16x32_bf16 v[22:25], v[166:169], v[206:209], 0
	v_mfma_f32_16x16x32_bf16 v[14:17], v[158:161], v[214:217], 0
	v_mfma_f32_16x16x32_bf16 v[2:5], v[166:169], v[214:217], 0
	v_mfma_f32_16x16x32_bf16 v[62:65], v[162:165], v[194:197], v[62:65]
	v_mfma_f32_16x16x32_bf16 v[54:57], v[170:173], v[194:197], v[54:57]
	v_mfma_f32_16x16x32_bf16 v[46:49], v[162:165], v[202:205], v[46:49]
	v_mfma_f32_16x16x32_bf16 v[38:41], v[170:173], v[202:205], v[38:41]
	v_mfma_f32_16x16x32_bf16 v[30:33], v[162:165], v[210:213], v[30:33]
	v_mfma_f32_16x16x32_bf16 v[22:25], v[170:173], v[210:213], v[22:25]
	v_mfma_f32_16x16x32_bf16 v[14:17], v[162:165], v[218:221], v[14:17]
	v_mfma_f32_16x16x32_bf16 v[2:5], v[170:173], v[218:221], v[2:5]
	s_setprio 0
	s_barrier
	s_add_i32 s84, 0, 0x18000
	s_add_i32 s85, 0, 0x1c000
	v_add_u32_e32 v154, s84, v148
	v_add_u32_e32 v170, s85, v148
	ds_read_b128 v[140:143], v154
	ds_read_b128 v[144:147], v154 offset:1024
	ds_read_b128 v[150:153], v154 offset:2048
	ds_read_b128 v[154:157], v154 offset:3072
	ds_read_b128 v[158:161], v170
	ds_read_b128 v[162:165], v170 offset:1024
	ds_read_b128 v[166:169], v170 offset:2048
	ds_read_b128 v[170:173], v170 offset:3072
	s_add_u32 s54, s54, 0x40000
	s_addc_u32 s55, s55, 0
	s_mov_b32 m0, s49
	v_lshl_add_u64 v[190:191], s[54:55], 0, v[136:137]
	ds_read_b128 v[174:177], v149 offset:32768
	ds_read_b128 v[194:197], v149 offset:33792
	ds_read_b128 v[198:201], v149 offset:34816
	ds_read_b128 v[202:205], v149 offset:35840
	ds_read_b128 v[206:209], v149 offset:36864
	ds_read_b128 v[210:213], v149 offset:37888
	ds_read_b128 v[214:217], v149 offset:38912
	ds_read_b128 v[218:221], v149 offset:39936
	global_load_lds_dwordx4 v[190:191], off
	v_lshl_add_u64 v[190:191], s[54:55], 0, v[132:133]
	s_mov_b32 m0, s53
	s_nop 0
	global_load_lds_dwordx4 v[190:191], off
	s_waitcnt vmcnt(8)
	s_waitcnt lgkmcnt(0)
	s_barrier
	s_setprio 1
	s_waitcnt lgkmcnt(0)
	v_mfma_f32_16x16x32_bf16 v[122:125], v[140:143], v[174:177], v[122:125]
	v_mfma_f32_16x16x32_bf16 v[114:117], v[150:153], v[174:177], v[114:117]
	v_mfma_f32_16x16x32_bf16 v[106:109], v[140:143], v[198:201], v[106:109]
	v_mfma_f32_16x16x32_bf16 v[98:101], v[150:153], v[198:201], v[98:101]
	v_mfma_f32_16x16x32_bf16 v[90:93], v[140:143], v[206:209], v[90:93]
	v_mfma_f32_16x16x32_bf16 v[82:85], v[150:153], v[206:209], v[82:85]
	v_mfma_f32_16x16x32_bf16 v[74:77], v[140:143], v[214:217], v[74:77]
	v_mfma_f32_16x16x32_bf16 v[66:69], v[150:153], v[214:217], v[66:69]
	v_mfma_f32_16x16x32_bf16 v[122:125], v[144:147], v[194:197], v[122:125]
	v_mfma_f32_16x16x32_bf16 v[114:117], v[154:157], v[194:197], v[114:117]
	v_mfma_f32_16x16x32_bf16 v[106:109], v[144:147], v[202:205], v[106:109]
	v_mfma_f32_16x16x32_bf16 v[98:101], v[154:157], v[202:205], v[98:101]
	v_mfma_f32_16x16x32_bf16 v[90:93], v[144:147], v[210:213], v[90:93]
	v_mfma_f32_16x16x32_bf16 v[82:85], v[154:157], v[210:213], v[82:85]
	v_mfma_f32_16x16x32_bf16 v[74:77], v[144:147], v[218:221], v[74:77]
	v_mfma_f32_16x16x32_bf16 v[66:69], v[154:157], v[218:221], v[66:69]
	s_setprio 0
	s_setprio 1
	v_mfma_f32_16x16x32_bf16 v[126:129], v[158:161], v[174:177], v[126:129]
	v_mfma_f32_16x16x32_bf16 v[118:121], v[166:169], v[174:177], v[118:121]
	v_mfma_f32_16x16x32_bf16 v[110:113], v[158:161], v[198:201], v[110:113]
	v_mfma_f32_16x16x32_bf16 v[102:105], v[166:169], v[198:201], v[102:105]
	v_mfma_f32_16x16x32_bf16 v[94:97], v[158:161], v[206:209], v[94:97]
	v_mfma_f32_16x16x32_bf16 v[86:89], v[166:169], v[206:209], v[86:89]
	v_mfma_f32_16x16x32_bf16 v[78:81], v[158:161], v[214:217], v[78:81]
	v_mfma_f32_16x16x32_bf16 v[70:73], v[166:169], v[214:217], v[70:73]
	v_mfma_f32_16x16x32_bf16 v[126:129], v[162:165], v[194:197], v[126:129]
	v_mfma_f32_16x16x32_bf16 v[118:121], v[170:173], v[194:197], v[118:121]
	v_mfma_f32_16x16x32_bf16 v[110:113], v[162:165], v[202:205], v[110:113]
	v_mfma_f32_16x16x32_bf16 v[102:105], v[170:173], v[202:205], v[102:105]
	v_mfma_f32_16x16x32_bf16 v[94:97], v[162:165], v[210:213], v[94:97]
	v_mfma_f32_16x16x32_bf16 v[86:89], v[170:173], v[210:213], v[86:89]
	v_mfma_f32_16x16x32_bf16 v[78:81], v[162:165], v[218:221], v[78:81]
	v_mfma_f32_16x16x32_bf16 v[70:73], v[170:173], v[218:221], v[70:73]
	s_setprio 0
	s_barrier
; #define PG8_STAGE(bufoff, gbase, voff) do { _Pragma("unroll") for (int _i = 0; _i < 2; ++_i) \
;         __builtin_amdgcn_global_load_lds((const unsigned*)((const char*)(gbase) + (voff)[_i]), (LAS unsigned*)(lds + (bufoff) + ldsw + _i * 8192), 16, 0, 0); } while (0)
; #define PG8_LDA(dst, b, h) do { _Pragma("unroll") for (int m = 0; m < 4; ++m) _Pragma("unroll") for (int k = 0; k < 2; ++k) dst[m][k] = *(const LAS bf16x8*)(lds + PG8_SA(b, h) + aoff + m * 2048 + k * 1024); } while (0)
; #define PG8_MMA(ai, bj, At, Bt) do { __builtin_amdgcn_s_setprio(1); _Pragma("unroll") for (int m = 0; m < 4; ++m) _Pragma("unroll") for (int n = 0; n < 2; ++n) _Pragma("unroll") for (int k = 0; k < 2; ++k) \
;         acc[ai][bj][m][n] = __builtin_amdgcn_mfma_f32_16x16x32_bf16(Bt[n][k], At[m][k], acc[ai][bj][m][n], 0, 0, 0); __builtin_amdgcn_s_setprio(0); } while (0)
; #define PG8_WAIT_V(n) asm volatile("s_waitcnt vmcnt(" #n ")" ::: "memory")
; #define PG8_WAIT_L(n) asm volatile("s_waitcnt lgkmcnt(" #n ")" ::: "memory")
; #define PG8_BAR __builtin_amdgcn_s_barrier()
; #define PG8_SCHED __builtin_amdgcn_sched_barrier(0)
; template <class Epi, class Pre, bool AG = false>
; __device__ __forceinline__ void gemm_phase(LAS unsigned char* lds, const Gemm g, const StaticOrder& S, const Epi& E, const Pre& P) {
;     ...
;         for (int t = 0; t < nt; t += 2) {
;     ...
;             PG8_LDA(At, 1, 1); PG8_STAGE(PG8_SB(1, 0), b3, voffB); PG8_STAGE(PG8_SB(1, 1), b3 + hstep, voffB); PG8_STAGE(PG8_SA(1, 0), a3, voffA);
;             PG8_WAIT_V(8); PG8_WAIT_L(0); PG8_BAR; PG8_MMA(1, 0, At, B0); PG8_MMA(1, 1, At, B1); PG8_BAR; PG8_SCHED;
	s_add_i32 s54, s84, s31
	v_lshl_add_u64 v[178:179], v[178:179], 0, s[66:67]
	s_mov_b32 m0, s54
	ds_read_b128 v[174:177], v149 offset:49152
	ds_read_b128 v[194:197], v149 offset:50176
	ds_read_b128 v[198:201], v149 offset:51200
	ds_read_b128 v[202:205], v149 offset:52224
	ds_read_b128 v[206:209], v149 offset:53248
	ds_read_b128 v[210:213], v149 offset:54272
	ds_read_b128 v[214:217], v149 offset:55296
	ds_read_b128 v[218:221], v149 offset:56320
	global_load_lds_dwordx4 v[178:179], off
	s_add_i32 m0, s54, 0x2000
	s_add_u32 s46, s46, 0x40080
	v_lshl_add_u64 v[178:179], v[180:181], 0, s[66:67]
	s_addc_u32 s47, s47, 0
	s_add_i32 s54, s85, s31
	global_load_lds_dwordx4 v[178:179], off
	v_lshl_add_u64 v[178:179], s[46:47], 0, v[134:135]
	s_mov_b32 m0, s54
	s_nop 0
	global_load_lds_dwordx4 v[178:179], off
	v_lshl_add_u64 v[178:179], s[46:47], 0, v[130:131]
	s_add_i32 m0, s54, 0x2000
	s_nop 0
	global_load_lds_dwordx4 v[178:179], off
	v_lshl_add_u64 v[178:179], v[182:183], 0, s[66:67]
	s_mov_b32 m0, s58
	s_nop 0
	global_load_lds_dwordx4 v[178:179], off
	v_lshl_add_u64 v[178:179], v[188:189], 0, s[66:67]
	s_mov_b32 m0, s59
	s_nop 0
	global_load_lds_dwordx4 v[178:179], off
	s_waitcnt vmcnt(8)
	s_waitcnt lgkmcnt(0)
	s_barrier
	s_setprio 1
	s_waitcnt lgkmcnt(0)
	v_mfma_f32_16x16x32_bf16 v[58:61], v[140:143], v[174:177], v[58:61]
	v_mfma_f32_16x16x32_bf16 v[50:53], v[150:153], v[174:177], v[50:53]
	v_mfma_f32_16x16x32_bf16 v[42:45], v[140:143], v[198:201], v[42:45]
	v_mfma_f32_16x16x32_bf16 v[34:37], v[150:153], v[198:201], v[34:37]
	v_mfma_f32_16x16x32_bf16 v[26:29], v[140:143], v[206:209], v[26:29]
	v_mfma_f32_16x16x32_bf16 v[18:21], v[150:153], v[206:209], v[18:21]
	v_mfma_f32_16x16x32_bf16 v[10:13], v[140:143], v[214:217], v[10:13]
	v_mfma_f32_16x16x32_bf16 v[6:9], v[150:153], v[214:217], v[6:9]
	v_mfma_f32_16x16x32_bf16 v[58:61], v[144:147], v[194:197], v[58:61]
	v_mfma_f32_16x16x32_bf16 v[50:53], v[154:157], v[194:197], v[50:53]
	v_mfma_f32_16x16x32_bf16 v[42:45], v[144:147], v[202:205], v[42:45]
	v_mfma_f32_16x16x32_bf16 v[34:37], v[154:157], v[202:205], v[34:37]
	v_mfma_f32_16x16x32_bf16 v[26:29], v[144:147], v[210:213], v[26:29]
	v_mfma_f32_16x16x32_bf16 v[18:21], v[154:157], v[210:213], v[18:21]
	v_mfma_f32_16x16x32_bf16 v[10:13], v[144:147], v[218:221], v[10:13]
	v_mfma_f32_16x16x32_bf16 v[6:9], v[154:157], v[218:221], v[6:9]
	s_setprio 0
	s_setprio 1
	v_mfma_f32_16x16x32_bf16 v[62:65], v[158:161], v[174:177], v[62:65]
	v_mfma_f32_16x16x32_bf16 v[54:57], v[166:169], v[174:177], v[54:57]
	v_mfma_f32_16x16x32_bf16 v[46:49], v[158:161], v[198:201], v[46:49]
	v_mfma_f32_16x16x32_bf16 v[38:41], v[166:169], v[198:201], v[38:41]
	v_mfma_f32_16x16x32_bf16 v[30:33], v[158:161], v[206:209], v[30:33]
	v_mfma_f32_16x16x32_bf16 v[22:25], v[166:169], v[206:209], v[22:25]
	v_mfma_f32_16x16x32_bf16 v[14:17], v[158:161], v[214:217], v[14:17]
	v_mfma_f32_16x16x32_bf16 v[2:5], v[166:169], v[214:217], v[2:5]
	v_mfma_f32_16x16x32_bf16 v[62:65], v[162:165], v[194:197], v[62:65]
	v_mfma_f32_16x16x32_bf16 v[54:57], v[170:173], v[194:197], v[54:57]
	v_mfma_f32_16x16x32_bf16 v[46:49], v[162:165], v[202:205], v[46:49]
	v_mfma_f32_16x16x32_bf16 v[38:41], v[170:173], v[202:205], v[38:41]
	v_mfma_f32_16x16x32_bf16 v[30:33], v[162:165], v[210:213], v[30:33]
	v_mfma_f32_16x16x32_bf16 v[22:25], v[170:173], v[210:213], v[22:25]
	v_mfma_f32_16x16x32_bf16 v[14:17], v[162:165], v[218:221], v[14:17]
	v_mfma_f32_16x16x32_bf16 v[2:5], v[170:173], v[218:221], v[2:5]
	s_setprio 0
	s_barrier
	s_add_i32 s79, s79, 2
	s_add_u32 s44, s44, 0x100
	s_addc_u32 s45, s45, 0
	s_add_u32 s76, s76, 0x100
	s_addc_u32 s77, s77, 0
	s_cmp_gt_u32 s79, 13
	s_cbranch_scc0 .LBB0_212
	s_branch .Lpeel_gu_after
